# v16 + pass2: norm step's LDS reads issued right behind barrier 1 (in front of the preparation), waits only on the last-chunk path
# baseline (speedup 1.0000x reference)
.LBB0_1329:
	s_or_b64 exec, exec, s[20:21]
	s_branch .LBB0_1330

.LBB0_1330:
	s_add_i32 s26, s26, 1
	s_mov_b64 s[20:21], 0x10000
	s_waitcnt vmcnt(4)
	v_add_f32_e32 v170, v148, v149
	v_add_f32_e32 v171, v150, v151
	v_add_f32_e32 v172, v152, v153
	v_add_f32_e32 v170, v170, v171
	v_add_f32_e32 v173, v154, v155
	v_add_f32_e32 v172, v172, v173
	v_add_f32_e32 v170, v170, v172
	v_fmamk_f32 v170, v170, 0x3c000000, v218
	v_rsq_f32_e32 v170, v170
	v_add_f32_e32 v174, v156, v157
	v_add_f32_e32 v175, v158, v159
	v_add_f32_e32 v176, v162, v163
	v_add_f32_e32 v174, v174, v175
	v_add_f32_e32 v177, v164, v165
	v_add_f32_e32 v176, v176, v177
	v_add_f32_e32 v174, v174, v176
	v_fmamk_f32 v174, v174, 0x3c000000, v218
	v_rsq_f32_e32 v174, v174
	v_lshlrev_b32_e32 v178, 16, v166
	v_and_b32_e32 v179, 0xffff0000, v166
	v_lshlrev_b32_e32 v200, 16, v167
	v_and_b32_e32 v201, 0xffff0000, v167
	v_lshlrev_b32_e32 v202, 16, v168
	v_and_b32_e32 v203, 0xffff0000, v168
	v_lshlrev_b32_e32 v204, 16, v169
	v_and_b32_e32 v205, 0xffff0000, v169
	v_mul_f32_e32 v206, v62, v170
	v_mul_f32_e32 v207, v63, v170
	v_mul_f32_e32 v208, v64, v170
	v_mul_f32_e32 v209, v65, v170
	v_mul_f32_e32 v210, v58, v174
	v_mul_f32_e32 v211, v59, v174
	v_mul_f32_e32 v212, v60, v174
	v_mul_f32_e32 v213, v61, v174
	v_mul_f32_e32 v206, v224, v206
	v_mul_f32_e32 v207, v225, v207
	v_mul_f32_e32 v208, v226, v208
	v_mul_f32_e32 v209, v227, v209
	v_mul_f32_e32 v210, v224, v210
	v_mul_f32_e32 v211, v225, v211
	v_mul_f32_e32 v212, v226, v212
	v_mul_f32_e32 v213, v227, v213
	v_mul_f32_e32 v206, v206, v178
	v_mul_f32_e32 v207, v207, v179
	v_mul_f32_e32 v208, v208, v200
	v_mul_f32_e32 v209, v209, v201
	v_mul_f32_e32 v210, v210, v202
	v_mul_f32_e32 v211, v211, v203
	v_mul_f32_e32 v212, v212, v204
	v_mul_f32_e32 v213, v213, v205
	v_cvt_pk_bf16_f32 v148, v206, v207
	v_cvt_pk_bf16_f32 v149, v208, v209
	v_cvt_pk_bf16_f32 v150, v210, v211
	v_cvt_pk_bf16_f32 v151, v212, v213
	ds_write_b64 v125, v[148:149] offset:8704
	ds_write_b64 v125, v[150:151] offset:13056
	s_cmp_lg_u32 s26, 8
	s_waitcnt lgkmcnt(0)
	s_barrier
	v_add3_u32 v58, s27, v93, v80
	ds_read_b128 v[58:61], v58 offset:8704
	s_waitcnt lgkmcnt(0)
	global_store_dwordx4 v[88:89], v[58:61], off
	v_lshl_add_u64 v[88:89], v[88:89], 0, s[20:21]
	s_mov_b64 s[20:21], 0x2c000
	v_lshl_add_u64 v[90:91], v[90:91], 0, s[20:21]
	s_cbranch_scc0 .LBB0_1325

.LBB0_1334:
	s_mul_i32 s22, s22, 0xe400
	s_add_i32 s27, s22, 0
	v_add3_u32 v147, s27, v104, v109
	s_add_i32 s29, s27, s19
	ds_read_b64 v[148:149], v147
	ds_read_b64 v[150:151], v147 offset:32
	ds_read_b64 v[152:153], v147 offset:4352
	ds_read_b64 v[154:155], v147 offset:4384
	ds_read_b64 v[196:197], v147 offset:8704
	ds_read_b64 v[198:199], v147 offset:8736
	ds_read_b64 v[200:201], v147 offset:13056
	ds_read_b64 v[202:203], v147 offset:13088
	v_cvt_pk_bf16_f32 v126, v26, v27
	v_cvt_pk_bf16_f32 v127, v28, v29
	v_cvt_pk_bf16_f32 v128, v30, v31
	v_cvt_pk_bf16_f32 v129, v32, v33
	ds_read_b64 v[156:157], v147 offset:64
	ds_read_b64 v[158:159], v147 offset:96
	ds_read_b64 v[160:161], v147 offset:4416
	ds_read_b64 v[162:163], v147 offset:4448
	ds_read_b64 v[204:205], v147 offset:8768
	ds_read_b64 v[206:207], v147 offset:8800
	ds_read_b64 v[208:209], v147 offset:13120
	ds_read_b64 v[210:211], v147 offset:13152
	v_cvt_pk_bf16_f32 v130, v34, v35
	v_cvt_pk_bf16_f32 v131, v36, v37
	v_cvt_pk_bf16_f32 v132, v38, v39
	v_cvt_pk_bf16_f32 v133, v40, v41
	s_waitcnt lgkmcnt(8)
	v_mfma_f32_16x16x32_bf16 v[62:65], v[126:129], v[148:151], 0
	v_mfma_f32_16x16x32_bf16 v[58:61], v[126:129], v[152:155], 0
	v_mfma_f32_16x16x32_bf16 v[164:167], v[196:199], v[148:151], 0
	v_mfma_f32_16x16x32_bf16 v[168:171], v[196:199], v[152:155], 0
	v_mfma_f32_16x16x32_bf16 v[172:175], v[200:203], v[152:155], 0
	ds_read_b64 v[148:149], v147 offset:128
	ds_read_b64 v[150:151], v147 offset:160
	ds_read_b64 v[152:153], v147 offset:4480
	ds_read_b64 v[154:155], v147 offset:4512
	ds_read_b64 v[196:197], v147 offset:8832
	ds_read_b64 v[198:199], v147 offset:8864
	ds_read_b64 v[200:201], v147 offset:13184
	ds_read_b64 v[202:203], v147 offset:13216
	v_cvt_pk_bf16_f32 v134, v42, v43
	v_cvt_pk_bf16_f32 v135, v44, v45
	v_cvt_pk_bf16_f32 v136, v46, v47
	v_cvt_pk_bf16_f32 v137, v48, v49
	s_waitcnt lgkmcnt(8)
	v_mfma_f32_16x16x32_bf16 v[62:65], v[130:133], v[156:159], v[62:65]
	v_mfma_f32_16x16x32_bf16 v[58:61], v[130:133], v[160:163], v[58:61]
	v_mfma_f32_16x16x32_bf16 v[164:167], v[204:207], v[156:159], v[164:167]
	v_mfma_f32_16x16x32_bf16 v[168:171], v[204:207], v[160:163], v[168:171]
	v_mfma_f32_16x16x32_bf16 v[172:175], v[208:211], v[160:163], v[172:175]
	ds_read_b64 v[156:157], v147 offset:192
	ds_read_b64 v[158:159], v147 offset:224
	ds_read_b64 v[160:161], v147 offset:4544
	ds_read_b64 v[162:163], v147 offset:4576
	ds_read_b64 v[204:205], v147 offset:8896
	ds_read_b64 v[206:207], v147 offset:8928
	ds_read_b64 v[208:209], v147 offset:13248
	ds_read_b64 v[210:211], v147 offset:13280
	v_cvt_pk_bf16_f32 v138, v50, v51
	v_cvt_pk_bf16_f32 v139, v52, v53
	v_cvt_pk_bf16_f32 v140, v54, v55
	v_cvt_pk_bf16_f32 v141, v56, v57
	s_waitcnt lgkmcnt(8)
	v_mfma_f32_16x16x32_bf16 v[62:65], v[134:137], v[148:151], v[62:65]
	v_mfma_f32_16x16x32_bf16 v[58:61], v[134:137], v[152:155], v[58:61]
	v_mfma_f32_16x16x32_bf16 v[164:167], v[196:199], v[148:151], v[164:167]
	v_mfma_f32_16x16x32_bf16 v[168:171], v[196:199], v[152:155], v[168:171]
	v_mfma_f32_16x16x32_bf16 v[172:175], v[200:203], v[152:155], v[172:175]
	v_add_u32_e32 v176, s27, v106
	v_add_u32_e32 v68, v176, v123
	ds_read_b64_tr_b16 v[66:67], v68 offset:37888
	ds_read_b64_tr_b16 v[68:69], v68 offset:43008
	s_waitcnt lgkmcnt(2)
	v_mfma_f32_16x16x32_bf16 v[62:65], v[138:141], v[156:159], v[62:65]
	v_mfma_f32_16x16x32_bf16 v[58:61], v[138:141], v[160:163], v[58:61]
	v_mfma_f32_16x16x32_bf16 v[164:167], v[204:207], v[156:159], v[164:167]
	v_mfma_f32_16x16x32_bf16 v[168:171], v[204:207], v[160:163], v[168:171]
	v_mfma_f32_16x16x32_bf16 v[172:175], v[208:211], v[160:163], v[172:175]
	v_add_u32_e32 v125, s27, v105
	v_add_u32_e32 v134, v176, v110
	v_mov_b32_e32 v177, s55
	v_mov_b32_e32 v72, v16
	v_mov_b32_e32 v73, v16
	s_nop 0
	v_cndmask_b32_e64 v165, 0, v165, s[6:7]
	v_cndmask_b32_e64 v166, v166, 0, s[8:9]
	v_cndmask_b32_e64 v167, v167, 0, s[10:11]
	v_cndmask_b32_e64 v164, v164, v177, s[4:5]
	v_cvt_pk_bf16_f32 v70, v164, v165
	v_cvt_pk_bf16_f32 v71, v166, v167
	v_cndmask_b32_e64 v172, v172, v177, s[4:5]
	v_cndmask_b32_e64 v173, v173, 0, s[12:13]
	v_cndmask_b32_e64 v174, v174, 0, s[14:15]
	v_cndmask_b32_e64 v175, v175, 0, s[16:17]
	s_waitcnt lgkmcnt(0)
	v_mfma_f32_16x16x32_bf16 v[62:65], v[66:69], v[70:73], v[62:65]
	v_cvt_pk_bf16_f32 v70, v168, v169
	v_cvt_pk_bf16_f32 v71, v170, v171
	v_cvt_pk_bf16_f32 v72, v172, v173
	v_cvt_pk_bf16_f32 v73, v174, v175
	s_nop 1
	v_mfma_f32_16x16x32_bf16 v[58:61], v[66:69], v[70:73], v[58:61]
	ds_read_b128 v[160:163], v125 offset:56832
	ds_read_b64_tr_b16 v[148:149], v134 offset:27648
	ds_read_b64_tr_b16 v[150:151], v134 offset:32768
	ds_read_b128 v[164:167], v125 offset:56896
	ds_read_b64_tr_b16 v[152:153], v134 offset:27680
	ds_read_b64_tr_b16 v[154:155], v134 offset:32800
	s_waitcnt lgkmcnt(3)
	v_pk_mul_f32 v[26:27], v[26:27], v[160:161]
	v_pk_mul_f32 v[28:29], v[28:29], v[162:163]
	ds_read_b128 v[168:171], v125 offset:56960
	ds_read_b64_tr_b16 v[156:157], v134 offset:27712
	ds_read_b64_tr_b16 v[158:159], v134 offset:32832
	v_mfma_f32_16x16x32_bf16 v[26:29], v[148:151], v[66:69], v[26:29]
	s_waitcnt lgkmcnt(3)
	v_pk_mul_f32 v[30:31], v[30:31], v[164:165]
	v_pk_mul_f32 v[32:33], v[32:33], v[166:167]
	ds_read_b128 v[160:163], v125 offset:57024
	ds_read_b64_tr_b16 v[148:149], v134 offset:27744
	ds_read_b64_tr_b16 v[150:151], v134 offset:32864
	v_mfma_f32_16x16x32_bf16 v[30:33], v[152:155], v[66:69], v[30:33]
	s_waitcnt lgkmcnt(3)
	v_pk_mul_f32 v[34:35], v[34:35], v[168:169]
	v_pk_mul_f32 v[36:37], v[36:37], v[170:171]
	ds_read_b128 v[164:167], v125 offset:57088
	ds_read_b64_tr_b16 v[152:153], v134 offset:27776
	ds_read_b64_tr_b16 v[154:155], v134 offset:32896
	v_mfma_f32_16x16x32_bf16 v[34:37], v[156:159], v[66:69], v[34:37]
	s_waitcnt lgkmcnt(3)
	v_pk_mul_f32 v[38:39], v[38:39], v[160:161]
	v_pk_mul_f32 v[40:41], v[40:41], v[162:163]
	ds_read_b128 v[168:171], v125 offset:57152
	ds_read_b64_tr_b16 v[156:157], v134 offset:27808
	ds_read_b64_tr_b16 v[158:159], v134 offset:32928
	v_mfma_f32_16x16x32_bf16 v[38:41], v[148:151], v[66:69], v[38:41]
	s_waitcnt lgkmcnt(3)
	v_pk_mul_f32 v[42:43], v[42:43], v[164:165]
	v_pk_mul_f32 v[44:45], v[44:45], v[166:167]
	ds_read_b128 v[160:163], v125 offset:57216
	ds_read_b64_tr_b16 v[148:149], v134 offset:27840
	ds_read_b64_tr_b16 v[150:151], v134 offset:32960
	v_mfma_f32_16x16x32_bf16 v[42:45], v[152:155], v[66:69], v[42:45]
	s_waitcnt lgkmcnt(3)
	v_pk_mul_f32 v[46:47], v[46:47], v[168:169]
	v_pk_mul_f32 v[48:49], v[48:49], v[170:171]
	ds_read_b128 v[164:167], v125 offset:57280
	ds_read_b64_tr_b16 v[152:153], v134 offset:27872
	ds_read_b64_tr_b16 v[154:155], v134 offset:32992
	v_mfma_f32_16x16x32_bf16 v[46:49], v[156:159], v[66:69], v[46:49]
	s_waitcnt lgkmcnt(3)
	v_pk_mul_f32 v[50:51], v[50:51], v[160:161]
	v_pk_mul_f32 v[52:53], v[52:53], v[162:163]
	s_nop 1
	v_mfma_f32_16x16x32_bf16 v[50:53], v[148:151], v[66:69], v[50:53]
	s_waitcnt lgkmcnt(0)
	v_pk_mul_f32 v[54:55], v[54:55], v[164:165]
	v_pk_mul_f32 v[56:57], v[56:57], v[166:167]
	s_nop 1
	v_mfma_f32_16x16x32_bf16 v[54:57], v[152:155], v[66:69], v[54:57]
	v_mul_f32_e32 v148, v62, v62
	v_mul_f32_e32 v149, v58, v58
	v_fmac_f32_e32 v148, v63, v63
	v_fmac_f32_e32 v149, v59, v59
	v_fmac_f32_e32 v148, v64, v64
	v_fmac_f32_e32 v149, v60, v60
	v_fmac_f32_e32 v148, v65, v65
	v_fmac_f32_e32 v149, v61, v61
	v_lshl_add_u32 v156, v77, 5, s29
	s_nop 0
	v_permlane16_swap_b32_e32 v148, v149
	v_add_f32_e32 v148, v148, v149
	v_mov_b32_e32 v149, v148
	s_nop 1
	v_permlane32_swap_b32_e32 v148, v149
	v_add_f32_e32 v148, v148, v149
	s_mov_b64 s[22:23], exec
	s_mov_b32 exec_hi, 0
	ds_write_b32 v156, v148 offset:57344
	s_mov_b64 exec, s[22:23]
	s_waitcnt lgkmcnt(0)
	s_barrier
	v_lshl_add_u32 v160, v95, 5, s27
	ds_read_b128 v[148:151], v160 offset:57344
	ds_read_b128 v[152:155], v160 offset:57360
	ds_read_b128 v[156:159], v160 offset:57856
	ds_read_b128 v[162:165], v160 offset:57872
	v_add3_u32 v125, s27, v109, v222
	ds_read_b64 v[166:167], v125 offset:48128
	ds_read_b64 v[168:169], v125 offset:52480
	s_andn2_b64 vcc, exec, s[20:21]
	s_cbranch_vccnz .Lp2_Fwait
	v_add3_u32 v68, s28, v96, v120
	ds_read_b64_tr_b16 v[66:67], v68 offset:17408
	ds_read_b64_tr_b16 v[68:69], v68 offset:18688
	v_add_u32_e32 v138, s28, v236
	v_add3_u32 v139, s28, v109, v222
	ds_read_b64 v[180:181], v138 offset:17408
	ds_read_b64 v[182:183], v138 offset:22528
	ds_read_b64 v[184:185], v139
	ds_read_b64 v[186:187], v139 offset:4352
	s_waitcnt lgkmcnt(4)
	v_mfma_f32_16x16x32_bf16 v[70:73], v[66:69], v[4:7], 0
	v_mfma_f32_16x16x32_bf16 v[66:69], v[66:69], v[0:3], 0
	s_mov_b32 s23, 0x42e60000
	s_waitcnt lgkmcnt(0)
	v_lshlrev_b32_e32 v188, 16, v180
	v_and_b32_e32 v189, 0xffff0000, v180
	v_lshlrev_b32_e32 v190, 16, v181
	v_and_b32_e32 v191, 0xffff0000, v181
	v_lshlrev_b32_e32 v192, 16, v182
	v_and_b32_e32 v193, 0xffff0000, v182
	v_lshlrev_b32_e32 v194, 16, v183
	v_and_b32_e32 v195, 0xffff0000, v183
	v_lshlrev_b32_e32 v196, 16, v184
	v_and_b32_e32 v197, 0xffff0000, v184
	v_lshlrev_b32_e32 v198, 16, v185
	v_and_b32_e32 v199, 0xffff0000, v185
	v_lshlrev_b32_e32 v200, 16, v186
	v_and_b32_e32 v201, 0xffff0000, v186
	v_lshlrev_b32_e32 v202, 16, v187
	v_and_b32_e32 v203, 0xffff0000, v187
	v_exp_f32_e32 v188, v188
	v_exp_f32_e32 v189, v189
	v_exp_f32_e32 v190, v190
	v_exp_f32_e32 v191, v191
	v_exp_f32_e32 v192, v192
	v_exp_f32_e32 v193, v193
	v_exp_f32_e32 v194, v194
	v_exp_f32_e32 v195, v195
	v_sub_f32_e32 v188, 1.0, v188
	v_sub_f32_e32 v189, 1.0, v189
	v_sub_f32_e32 v190, 1.0, v190
	v_sub_f32_e32 v191, 1.0, v191
	v_sub_f32_e32 v192, 1.0, v192
	v_sub_f32_e32 v193, 1.0, v193
	v_sub_f32_e32 v194, 1.0, v194
	v_sub_f32_e32 v195, 1.0, v195
	v_exp_f32_e32 v204, v70
	v_exp_f32_e32 v205, v71
	v_exp_f32_e32 v206, v72
	v_exp_f32_e32 v207, v73
	v_exp_f32_e32 v208, v66
	v_exp_f32_e32 v209, v67
	v_exp_f32_e32 v210, v68
	v_exp_f32_e32 v211, v69
	v_sub_f32_dpp v126, v66, v70 row_newbcast:15 row_mask:0xf bank_mask:0xf
	v_sub_f32_dpp v127, v67, v71 row_newbcast:15 row_mask:0xf bank_mask:0xf
	v_sub_f32_dpp v128, v68, v72 row_newbcast:15 row_mask:0xf bank_mask:0xf
	v_sub_f32_dpp v129, v69, v73 row_newbcast:15 row_mask:0xf bank_mask:0xf
	v_sub_f32_dpp v130, v66, v66 row_newbcast:15 row_mask:0xf bank_mask:0xf
	v_sub_f32_dpp v131, v67, v67 row_newbcast:15 row_mask:0xf bank_mask:0xf
	v_sub_f32_dpp v132, v68, v68 row_newbcast:15 row_mask:0xf bank_mask:0xf
	v_sub_f32_dpp v133, v69, v69 row_newbcast:15 row_mask:0xf bank_mask:0xf
	v_mul_f32_e32 v196, v196, v204
	v_mul_f32_e32 v197, v197, v205
	v_mul_f32_e32 v198, v198, v206
	v_mul_f32_e32 v199, v199, v207
	v_mul_f32_e32 v200, v200, v208
	v_mul_f32_e32 v201, v201, v209
	v_mul_f32_e32 v202, v202, v210
	v_mul_f32_e32 v203, v203, v211
	v_min_f32_e64 v204, -v70, s23
	v_min_f32_e64 v205, -v71, s23
	v_min_f32_e64 v206, -v72, s23
	v_min_f32_e64 v207, -v73, s23
	v_min_f32_e64 v208, -v66, s23
	v_min_f32_e64 v209, -v67, s23
	v_min_f32_e64 v210, -v68, s23
	v_min_f32_e64 v211, -v69, s23
	v_exp_f32_e32 v126, v126
	v_exp_f32_e32 v127, v127
	v_exp_f32_e32 v128, v128
	v_exp_f32_e32 v129, v129
	v_exp_f32_e32 v130, v130
	v_exp_f32_e32 v131, v131
	v_exp_f32_e32 v132, v132
	v_exp_f32_e32 v133, v133
	v_exp_f32_e32 v204, v204
	v_exp_f32_e32 v205, v205
	v_exp_f32_e32 v206, v206
	v_exp_f32_e32 v207, v207
	v_exp_f32_e32 v208, v208
	v_exp_f32_e32 v209, v209
	v_exp_f32_e32 v210, v210
	v_exp_f32_e32 v211, v211
	v_exp_f32_e32 v212, v66
	v_exp_f32_e32 v213, v67
	v_exp_f32_e32 v214, v68
	v_exp_f32_e32 v215, v69
	v_mul_f32_e32 v126, v126, v188
	v_mul_f32_e32 v127, v127, v189
	v_mul_f32_e32 v128, v128, v190
	v_mul_f32_e32 v129, v129, v191
	v_mul_f32_e32 v130, v130, v192
	v_mul_f32_e32 v131, v131, v193
	v_mul_f32_e32 v132, v132, v194
	v_mul_f32_e32 v133, v133, v195
	v_mul_f32_e32 v204, v204, v188
	v_mul_f32_e32 v205, v205, v189
	v_mul_f32_e32 v206, v206, v190
	v_mul_f32_e32 v207, v207, v191
	v_mul_f32_e32 v208, v208, v192
	v_mul_f32_e32 v209, v209, v193
	v_mul_f32_e32 v210, v210, v194
	v_mul_f32_e32 v211, v211, v195
	v_lshl_add_u32 v216, v222, 1, s28
	v_cvt_pk_bf16_f32 v180, v196, v197
	v_cvt_pk_bf16_f32 v181, v198, v199
	v_cvt_pk_bf16_f32 v182, v200, v201
	v_cvt_pk_bf16_f32 v183, v202, v203
	v_cvt_pk_bf16_f32 v184, v204, v205
	v_cvt_pk_bf16_f32 v185, v206, v207
	v_cvt_pk_bf16_f32 v186, v208, v209
	v_cvt_pk_bf16_f32 v187, v210, v211
	v_cvt_pk_bf16_f32 v134, v126, v127
	v_cvt_pk_bf16_f32 v135, v128, v129
	v_cvt_pk_bf16_f32 v136, v130, v131
	v_cvt_pk_bf16_f32 v137, v132, v133
	ds_write_b64 v139, v[180:181]
	ds_write_b64 v139, v[182:183] offset:4352
	ds_write_b64 v139, v[184:185] offset:8704
	ds_write_b64 v139, v[186:187] offset:13056
	ds_write_b64 v138, v[134:135] offset:27648
	ds_write_b64 v138, v[136:137] offset:32768
	s_and_saveexec_b64 s[20:21], s[2:3]
	ds_write_b128 v216, v[212:215] offset:56832
	s_branch .LBB0_1329
